# GEMM phase prologues: second DMA group (K-tile 1) issued before waiting for K-tile 0; wait(2)+barrier became wait(8)+barrier after the 6 loads
# speedup vs baseline: 1.0092x; 1.0092x over previous
; #define PG8_STAGE(bufoff, gbase, voff) do { _Pragma("unroll") for (int _i = 0; _i < 2; ++_i) \
;         __builtin_amdgcn_global_load_lds((const unsigned*)((const char*)(gbase) + (voff)[_i]), (PG8_LAS unsigned*)(lds + (bufoff) + ldsw + _i * 8192), 16, 0, 0); } while (0)
; #define PG8_WAIT_V(n) asm volatile("s_waitcnt vmcnt(" #n ")" ::: "memory")
; #define PG8_BAR __builtin_amdgcn_s_barrier()
; template <class Epi, class Sched, bool ALIGN_EPI = false, bool SP2 = false>
; __device__ __forceinline__ void gemm_phase(PG8_LAS unsigned char* lds, const Gemm g, const Sched& S, const Epi& E) {
;     ...
;     f32x4 acc[2][2][4][2];
; #pragma unroll
;     for (int a = 0; a < 2; ++a)
; #pragma unroll
;         for (int b = 0; b < 2; ++b)
; #pragma unroll
;             for (int m = 0; m < 4; ++m)
; #pragma unroll
;                 for (int n = 0; n < 2; ++n) acc[a][b][m][n] = (f32x4){0.f, 0.f, 0.f, 0.f};
;     ...
;         PG8_STAGE(PG8_SB(0, 0), cB, voffB); PG8_STAGE(PG8_SB(0, 1), cB + hstep, voffB); PG8_STAGE(PG8_SA(0, 0), cA, voffA); PG8_STAGE(PG8_SA(0, 1), cA + hstep, voffA);
;         if (wr == 1) PG8_BAR;
;         PG8_WAIT_V(2); PG8_BAR;
;         PG8_STAGE(PG8_SB(1, 0), cB + kstep, voffB); PG8_STAGE(PG8_SA(1, 0), cA + kstep, voffA); PG8_STAGE(PG8_SB(1, 1), cB + hstep + kstep, voffB);
;         PG8_WAIT_V(6); PG8_BAR;
.LBB0_188:
	v_mov_b32_e32 v141, v1
	v_lshl_add_u64 v[12:13], s[10:11], 0, v[140:141]
	v_mov_b32_e32 v137, v1
	v_lshl_add_u64 v[14:15], s[10:11], 0, v[136:137]
	v_mov_b32_e32 v143, v1
	s_add_i32 m0, s42, 0x18000
	v_lshl_add_u64 v[12:13], v[12:13], 0, s[24:25]
	v_lshl_add_u64 v[20:21], s[12:13], 0, v[142:143]
	v_mov_b32_e32 v139, v1
	global_load_lds_dwordx4 v[12:13], off
	v_lshl_add_u64 v[12:13], v[14:15], 0, s[24:25]
	s_add_i32 m0, s42, 0x1a000
	s_add_i32 s52, s42, 0x8000
	v_lshl_add_u64 v[22:23], s[12:13], 0, v[138:139]
	global_load_lds_dwordx4 v[12:13], off
	v_lshl_add_u64 v[12:13], v[20:21], 0, s[24:25]
	s_mov_b32 m0, s52
	s_add_i32 s53, s42, 0xa000
	v_lshl_add_u64 v[16:17], s[2:3], 0, v[140:141]
	global_load_lds_dwordx4 v[12:13], off
	v_lshl_add_u64 v[12:13], v[22:23], 0, s[24:25]
	s_mov_b32 m0, s53
	v_lshl_add_u64 v[18:19], s[2:3], 0, v[136:137]
	global_load_lds_dwordx4 v[12:13], off
	s_add_i32 m0, s42, 0x1c000
	v_lshl_add_u64 v[12:13], v[16:17], 0, s[24:25]
	global_load_lds_dwordx4 v[12:13], off
	v_lshl_add_u64 v[12:13], v[18:19], 0, s[24:25]
	s_add_i32 m0, s42, 0x1e000
	v_and_b32_e32 v11, 15, v149
	global_load_lds_dwordx4 v[12:13], off
	s_waitcnt vmcnt(8)
	s_barrier
	v_and_b32_e32 v12, 48, v149
	v_add_u32_e32 v0, v10, v0
	v_lshl_or_b32 v148, s4, 6, v11
	v_lshl_or_b32 v11, v11, 6, v12
	v_lshlrev_b32_e32 v12, 2, v149
	v_add_lshl_u32 v0, v0, v9, 1
	s_and_b32 s43, s5, 3
	s_lshl_b32 s2, s4, 13
	v_and_b32_e32 v12, 32, v12
	v_lshl_add_u64 v[144:145], s[48:49], 0, v[0:1]
	v_add_u32_e32 v0, v8, v2
	v_bitop3_b32 v13, v11, s2, v12 bitop3:0xde
	s_lshl_b32 s2, s43, 12
	s_waitcnt vmcnt(6)
	v_add_lshl_u32 v0, v0, v3, 1
	v_mov_b32_e32 v2, v1
	v_mov_b32_e32 v3, v1
	v_bitop3_b32 v150, v11, s2, v12 bitop3:0xde
	v_lshl_add_u64 v[146:147], s[48:49], 0, v[0:1]
	v_mov_b32_e32 v0, v1
	v_add_u32_e32 v151, 0, v13
	v_mov_b64_e32 v[10:11], v[2:3]
	v_mov_b64_e32 v[14:15], v[2:3]
	v_mov_b64_e32 v[26:27], v[2:3]
	v_mov_b64_e32 v[30:31], v[2:3]
	s_waitcnt vmcnt(0)
	v_mov_b64_e32 v[42:43], v[2:3]
	v_mov_b64_e32 v[46:47], v[2:3]
	v_mov_b64_e32 v[58:59], v[2:3]
	v_mov_b64_e32 v[62:63], v[2:3]
	v_mov_b64_e32 v[18:19], v[2:3]
	v_mov_b64_e32 v[22:23], v[2:3]
	v_mov_b64_e32 v[34:35], v[2:3]
	v_mov_b64_e32 v[38:39], v[2:3]
	v_mov_b64_e32 v[50:51], v[2:3]
	v_mov_b64_e32 v[54:55], v[2:3]
	v_mov_b64_e32 v[66:67], v[2:3]
	v_mov_b64_e32 v[70:71], v[2:3]
	v_mov_b64_e32 v[74:75], v[2:3]
	v_mov_b64_e32 v[78:79], v[2:3]
	v_mov_b64_e32 v[90:91], v[2:3]
	v_mov_b64_e32 v[94:95], v[2:3]
	v_mov_b64_e32 v[106:107], v[2:3]
	v_mov_b64_e32 v[110:111], v[2:3]
	v_mov_b64_e32 v[122:123], v[2:3]
	v_mov_b64_e32 v[126:127], v[2:3]
	v_mov_b64_e32 v[82:83], v[2:3]
	v_mov_b64_e32 v[86:87], v[2:3]
	v_mov_b64_e32 v[98:99], v[2:3]
	v_mov_b64_e32 v[102:103], v[2:3]
	v_mov_b64_e32 v[114:115], v[2:3]
	v_mov_b64_e32 v[118:119], v[2:3]
	v_mov_b64_e32 v[130:131], v[2:3]
	v_mov_b64_e32 v[134:135], v[2:3]
	s_mov_b32 s72, 0
	v_mov_b64_e32 v[8:9], v[0:1]
	v_mov_b64_e32 v[12:13], v[0:1]
	v_mov_b64_e32 v[24:25], v[0:1]
	v_mov_b64_e32 v[28:29], v[0:1]
	v_mov_b64_e32 v[40:41], v[0:1]
	v_mov_b64_e32 v[44:45], v[0:1]
	v_mov_b64_e32 v[56:57], v[0:1]
	v_mov_b64_e32 v[60:61], v[0:1]
	v_mov_b64_e32 v[16:17], v[0:1]
	v_mov_b64_e32 v[20:21], v[0:1]
	v_mov_b64_e32 v[32:33], v[0:1]
	v_mov_b64_e32 v[36:37], v[0:1]
	v_mov_b64_e32 v[48:49], v[0:1]
	v_mov_b64_e32 v[52:53], v[0:1]
	v_mov_b64_e32 v[64:65], v[0:1]
	v_mov_b64_e32 v[68:69], v[0:1]
	v_mov_b64_e32 v[72:73], v[0:1]
	v_mov_b64_e32 v[76:77], v[0:1]
	v_mov_b64_e32 v[88:89], v[0:1]
	v_mov_b64_e32 v[92:93], v[0:1]
	v_mov_b64_e32 v[104:105], v[0:1]
	v_mov_b64_e32 v[108:109], v[0:1]
	v_mov_b64_e32 v[120:121], v[0:1]
	v_mov_b64_e32 v[124:125], v[0:1]
	v_mov_b64_e32 v[80:81], v[0:1]
	v_mov_b64_e32 v[84:85], v[0:1]
	v_mov_b64_e32 v[96:97], v[0:1]
	v_mov_b64_e32 v[100:101], v[0:1]
	v_mov_b64_e32 v[112:113], v[0:1]
	v_mov_b64_e32 v[116:117], v[0:1]
	v_mov_b64_e32 v[128:129], v[0:1]
	v_mov_b64_e32 v[132:133], v[0:1]
	s_barrier
	s_branch .LBB0_190

; #define PG8_STAGE(bufoff, gbase, voff) do { _Pragma("unroll") for (int _i = 0; _i < 2; ++_i) \
;         __builtin_amdgcn_global_load_lds((const unsigned*)((const char*)(gbase) + (voff)[_i]), (PG8_LAS unsigned*)(lds + (bufoff) + ldsw + _i * 8192), 16, 0, 0); } while (0)
; #define PG8_WAIT_V(n) asm volatile("s_waitcnt vmcnt(" #n ")" ::: "memory")
; #define PG8_BAR __builtin_amdgcn_s_barrier()
; template <class Epi, class Sched, bool ALIGN_EPI = false, bool SP2 = false>
; __device__ __forceinline__ void gemm_phase(PG8_LAS unsigned char* lds, const Gemm g, const Sched& S, const Epi& E) {
;     ...
;     f32x4 acc[2][2][4][2];
; #pragma unroll
;     for (int a = 0; a < 2; ++a)
; #pragma unroll
;         for (int b = 0; b < 2; ++b)
; #pragma unroll
;             for (int m = 0; m < 4; ++m)
; #pragma unroll
;                 for (int n = 0; n < 2; ++n) acc[a][b][m][n] = (f32x4){0.f, 0.f, 0.f, 0.f};
;     ...
;         PG8_STAGE(PG8_SB(0, 0), cB, voffB); PG8_STAGE(PG8_SB(0, 1), cB + hstep, voffB); PG8_STAGE(PG8_SA(0, 0), cA, voffA); PG8_STAGE(PG8_SA(0, 1), cA + hstep, voffA);
;         if (wr == 1) PG8_BAR;
;         PG8_WAIT_V(2); PG8_BAR;
;         PG8_STAGE(PG8_SB(1, 0), cB + kstep, voffB); PG8_STAGE(PG8_SA(1, 0), cA + kstep, voffA); PG8_STAGE(PG8_SB(1, 1), cB + hstep + kstep, voffB);
;         PG8_WAIT_V(6); PG8_BAR;
.LBB0_233:
	v_and_b32_e32 v146, 15, v145
	v_mov_b32_e32 v139, v1
	v_and_b32_e32 v26, 48, v145
	v_lshlrev_b32_e32 v27, 2, v146
	v_lshl_add_u64 v[18:19], s[2:3], 0, v[0:1]
	v_lshl_add_u64 v[20:21], s[2:3], 0, v[138:139]
	s_and_b32 s45, s5, 3
	s_lshl_b32 s2, s4, 13
	v_lshl_or_b32 v26, v146, 6, v26
	v_and_b32_e32 v28, 32, v27
	v_bitop3_b32 v29, v26, s2, v28 bitop3:0xde
	s_lshl_b32 s2, s45, 12
	v_lshl_add_u64 v[14:15], s[10:11], 0, v[0:1]
	s_cmp_eq_u32 s33, 0
	v_lshl_add_u64 v[16:17], s[10:11], 0, v[138:139]
	v_mov_b32_e32 v3, v1
	s_cselect_b64 s[12:13], -1, 0
	s_add_i32 m0, s47, 0x18000
	v_lshl_add_u64 v[14:15], v[14:15], 0, s[24:25]
	v_lshl_add_u64 v[22:23], s[6:7], 0, v[2:3]
	v_mov_b32_e32 v137, v1
	global_load_lds_dwordx4 v[14:15], off
	v_lshl_add_u64 v[14:15], v[16:17], 0, s[24:25]
	s_add_i32 m0, s47, 0x1a000
	s_add_i32 s75, s47, 0x8000
	v_lshl_add_u64 v[24:25], s[6:7], 0, v[136:137]
	global_load_lds_dwordx4 v[14:15], off
	v_lshl_add_u64 v[14:15], v[22:23], 0, s[24:25]
	s_mov_b32 m0, s75
	s_add_i32 s76, s47, 0xa000
	global_load_lds_dwordx4 v[14:15], off
	v_lshl_add_u64 v[14:15], v[24:25], 0, s[24:25]
	s_mov_b32 m0, s76
	v_add_u32_e32 v8, v10, v8
	global_load_lds_dwordx4 v[14:15], off
	s_add_i32 m0, s47, 0x1c000
	v_lshl_add_u64 v[14:15], v[18:19], 0, s[24:25]
	global_load_lds_dwordx4 v[14:15], off
	v_lshl_add_u64 v[14:15], v[20:21], 0, s[24:25]
	s_add_i32 m0, s47, 0x1e000
	v_add_lshl_u32 v8, v8, v9, 1
	global_load_lds_dwordx4 v[14:15], off
	s_waitcnt vmcnt(8)
	s_barrier
	v_mov_b32_e32 v9, v1
	v_bitop3_b32 v147, v26, s2, v28 bitop3:0xde
	s_and_b32 s2, s1, 0xffffff00
	v_lshl_add_u64 v[140:141], s[48:49], 0, v[8:9]
	v_add_u32_e32 v8, v13, v11
	s_waitcnt vmcnt(6)
	s_add_i32 s73, s2, 0
	v_add_lshl_u32 v8, v8, v12, 1
	s_add_i32 s2, s73, 0x22d00
	v_lshl_add_u64 v[142:143], s[48:49], 0, v[8:9]
	v_mov_b32_e32 v8, 0
	v_lshl_or_b32 v144, s4, 6, v146
	s_mov_b32 s74, 0
	v_add_u32_e32 v148, s2, v27
	v_add_u32_e32 v149, 0, v29
	v_mov_b32_e32 v9, v8
	v_mov_b32_e32 v10, v8
	v_mov_b32_e32 v11, v8
	v_mov_b32_e32 v12, v8
	v_mov_b32_e32 v13, v8
	v_mov_b32_e32 v14, v8
	v_mov_b32_e32 v15, v8
	v_mov_b32_e32 v24, v8
	v_mov_b32_e32 v25, v8
	v_mov_b32_e32 v26, v8
	v_mov_b32_e32 v27, v8
	v_mov_b32_e32 v28, v8
	v_mov_b32_e32 v29, v8
	v_mov_b32_e32 v30, v8
	v_mov_b32_e32 v31, v8
	s_waitcnt vmcnt(0)
	v_mov_b32_e32 v40, v8
	v_mov_b32_e32 v41, v8
	v_mov_b32_e32 v42, v8
	v_mov_b32_e32 v43, v8
	v_mov_b32_e32 v44, v8
	v_mov_b32_e32 v45, v8
	v_mov_b32_e32 v46, v8
	v_mov_b32_e32 v47, v8
	v_mov_b32_e32 v56, v8
	v_mov_b32_e32 v57, v8
	v_mov_b32_e32 v58, v8
	v_mov_b32_e32 v59, v8
	v_mov_b32_e32 v60, v8
	v_mov_b32_e32 v61, v8
	v_mov_b32_e32 v62, v8
	v_mov_b32_e32 v63, v8
	v_mov_b32_e32 v16, v8
	v_mov_b32_e32 v17, v8
	v_mov_b32_e32 v18, v8
	v_mov_b32_e32 v19, v8
	v_mov_b32_e32 v20, v8
	v_mov_b32_e32 v21, v8
	v_mov_b32_e32 v22, v8
	v_mov_b32_e32 v23, v8
	v_mov_b32_e32 v32, v8
	v_mov_b32_e32 v33, v8
	v_mov_b32_e32 v34, v8
	v_mov_b32_e32 v35, v8
	v_mov_b32_e32 v36, v8
	v_mov_b32_e32 v37, v8
	v_mov_b32_e32 v38, v8
	v_mov_b32_e32 v39, v8
	v_mov_b32_e32 v48, v8
	v_mov_b32_e32 v49, v8
	v_mov_b32_e32 v50, v8
	v_mov_b32_e32 v51, v8
	v_mov_b32_e32 v52, v8
	v_mov_b32_e32 v53, v8
	v_mov_b32_e32 v54, v8
	v_mov_b32_e32 v55, v8
	v_mov_b32_e32 v64, v8
	v_mov_b32_e32 v65, v8
	v_mov_b32_e32 v66, v8
	v_mov_b32_e32 v67, v8
	v_mov_b32_e32 v68, v8
	v_mov_b32_e32 v69, v8
	v_mov_b32_e32 v70, v8
	v_mov_b32_e32 v71, v8
	v_mov_b32_e32 v72, v8
	v_mov_b32_e32 v73, v8
	v_mov_b32_e32 v74, v8
	v_mov_b32_e32 v75, v8
	v_mov_b32_e32 v76, v8
	v_mov_b32_e32 v77, v8
	v_mov_b32_e32 v78, v8
	v_mov_b32_e32 v79, v8
	v_mov_b32_e32 v88, v8
	v_mov_b32_e32 v89, v8
	v_mov_b32_e32 v90, v8
	v_mov_b32_e32 v91, v8
	v_mov_b32_e32 v92, v8
	v_mov_b32_e32 v93, v8
	v_mov_b32_e32 v94, v8
	v_mov_b32_e32 v95, v8
	v_mov_b32_e32 v104, v8
	v_mov_b32_e32 v105, v8
	v_mov_b32_e32 v106, v8
	v_mov_b32_e32 v107, v8
	v_mov_b32_e32 v108, v8
	v_mov_b32_e32 v109, v8
	v_mov_b32_e32 v110, v8
	v_mov_b32_e32 v111, v8
	v_mov_b32_e32 v120, v8
	v_mov_b32_e32 v121, v8
	v_mov_b32_e32 v122, v8
	v_mov_b32_e32 v123, v8
	v_mov_b32_e32 v124, v8
	v_mov_b32_e32 v125, v8
	v_mov_b32_e32 v126, v8
	v_mov_b32_e32 v127, v8
	v_mov_b32_e32 v80, v8
	v_mov_b32_e32 v81, v8
	v_mov_b32_e32 v82, v8
	v_mov_b32_e32 v83, v8
	v_mov_b32_e32 v84, v8
	v_mov_b32_e32 v85, v8
	v_mov_b32_e32 v86, v8
	v_mov_b32_e32 v87, v8
	v_mov_b32_e32 v96, v8
	v_mov_b32_e32 v97, v8
	v_mov_b32_e32 v98, v8
	v_mov_b32_e32 v99, v8
	v_mov_b32_e32 v100, v8
	v_mov_b32_e32 v101, v8
	v_mov_b32_e32 v102, v8
	v_mov_b32_e32 v103, v8
	v_mov_b32_e32 v112, v8
	v_mov_b32_e32 v113, v8
	v_mov_b32_e32 v114, v8
	v_mov_b32_e32 v115, v8
	v_mov_b32_e32 v116, v8
	v_mov_b32_e32 v117, v8
	v_mov_b32_e32 v118, v8
	v_mov_b32_e32 v119, v8
	v_mov_b32_e32 v128, v8
	v_mov_b32_e32 v129, v8
	v_mov_b32_e32 v130, v8
	v_mov_b32_e32 v131, v8
	v_mov_b32_e32 v132, v8
	v_mov_b32_e32 v133, v8
	v_mov_b32_e32 v134, v8
	v_mov_b32_e32 v135, v8
	s_barrier
	s_branch .LBB0_235

; #define PG8_STAGE(bufoff, gbase, voff) do { _Pragma("unroll") for (int _i = 0; _i < 2; ++_i) \
;         __builtin_amdgcn_global_load_lds((const unsigned*)((const char*)(gbase) + (voff)[_i]), (PG8_LAS unsigned*)(lds + (bufoff) + ldsw + _i * 8192), 16, 0, 0); } while (0)
; #define PG8_WAIT_V(n) asm volatile("s_waitcnt vmcnt(" #n ")" ::: "memory")
; #define PG8_BAR __builtin_amdgcn_s_barrier()
; template <class Epi, class Sched, bool ALIGN_EPI = false, bool SP2 = false>
; __device__ __forceinline__ void gemm_phase(PG8_LAS unsigned char* lds, const Gemm g, const Sched& S, const Epi& E) {
;     ...
;     f32x4 acc[2][2][4][2];
; #pragma unroll
;     for (int a = 0; a < 2; ++a)
; #pragma unroll
;         for (int b = 0; b < 2; ++b)
; #pragma unroll
;             for (int m = 0; m < 4; ++m)
; #pragma unroll
;                 for (int n = 0; n < 2; ++n) acc[a][b][m][n] = (f32x4){0.f, 0.f, 0.f, 0.f};
;     ...
;         PG8_STAGE(PG8_SB(0, 0), cB, voffB); PG8_STAGE(PG8_SB(0, 1), cB + hstep, voffB); PG8_STAGE(PG8_SA(0, 0), cA, voffA); PG8_STAGE(PG8_SA(0, 1), cA + hstep, voffA);
;         if (wr == 1) PG8_BAR;
;         PG8_WAIT_V(2); PG8_BAR;
;         PG8_STAGE(PG8_SB(1, 0), cB + kstep, voffB); PG8_STAGE(PG8_SA(1, 0), cA + kstep, voffA); PG8_STAGE(PG8_SB(1, 1), cB + hstep + kstep, voffB);
;         PG8_WAIT_V(6); PG8_BAR;
.LBB0_280:
	v_mov_b32_e32 v141, v1
	v_lshl_add_u64 v[12:13], s[0:1], 0, v[140:141]
	v_mov_b32_e32 v137, v1
	v_lshl_add_u64 v[14:15], s[0:1], 0, v[136:137]
	v_mov_b32_e32 v143, v1
	s_add_i32 m0, s46, 0x18000
	v_lshl_add_u64 v[12:13], v[12:13], 0, s[24:25]
	v_lshl_add_u64 v[20:21], s[16:17], 0, v[142:143]
	v_mov_b32_e32 v139, v1
	global_load_lds_dwordx4 v[12:13], off
	v_lshl_add_u64 v[12:13], v[14:15], 0, s[24:25]
	s_add_i32 m0, s46, 0x1a000
	s_add_i32 s73, s46, 0x8000
	v_lshl_add_u64 v[22:23], s[16:17], 0, v[138:139]
	global_load_lds_dwordx4 v[12:13], off
	v_lshl_add_u64 v[12:13], v[20:21], 0, s[24:25]
	s_mov_b32 m0, s73
	s_add_i32 s74, s46, 0xa000
	v_lshl_add_u64 v[16:17], s[2:3], 0, v[140:141]
	global_load_lds_dwordx4 v[12:13], off
	v_lshl_add_u64 v[12:13], v[22:23], 0, s[24:25]
	s_mov_b32 m0, s74
	v_lshl_add_u64 v[18:19], s[2:3], 0, v[136:137]
	global_load_lds_dwordx4 v[12:13], off
	s_add_i32 m0, s46, 0x1c000
	v_lshl_add_u64 v[12:13], v[16:17], 0, s[24:25]
	global_load_lds_dwordx4 v[12:13], off
	v_lshl_add_u64 v[12:13], v[18:19], 0, s[24:25]
	s_add_i32 m0, s46, 0x1e000
	v_add_u32_e32 v0, v10, v0
	global_load_lds_dwordx4 v[12:13], off
	s_waitcnt vmcnt(8)
	s_barrier
	v_and_b32_e32 v148, 15, v150
	v_and_b32_e32 v11, 48, v150
	v_lshlrev_b32_e32 v12, 2, v150
	v_add_lshl_u32 v0, v0, v9, 1
	s_and_b32 s72, s20, 3
	s_lshl_b32 s2, s4, 13
	v_lshl_or_b32 v11, v148, 6, v11
	v_and_b32_e32 v12, 32, v12
	v_lshl_add_u64 v[144:145], s[48:49], 0, v[0:1]
	v_add_u32_e32 v0, v8, v2
	v_bitop3_b32 v13, v11, s2, v12 bitop3:0xde
	s_lshl_b32 s2, s72, 12
	s_waitcnt vmcnt(6)
	v_add_lshl_u32 v0, v0, v3, 1
	v_mov_b32_e32 v2, v1
	v_mov_b32_e32 v3, v1
	v_bitop3_b32 v151, v11, s2, v12 bitop3:0xde
	v_lshl_add_u64 v[146:147], s[48:49], 0, v[0:1]
	v_mov_b32_e32 v0, v1
	v_add_u32_e32 v152, 0, v13
	v_mov_b64_e32 v[34:35], v[2:3]
	v_mov_b64_e32 v[38:39], v[2:3]
	v_mov_b64_e32 v[82:83], v[2:3]
	v_mov_b64_e32 v[86:87], v[2:3]
	v_mov_b64_e32 v[94:95], v[2:3]
	v_mov_b64_e32 v[90:91], v[2:3]
	s_waitcnt vmcnt(0)
	v_mov_b64_e32 v[46:47], v[2:3]
	v_mov_b64_e32 v[42:43], v[2:3]
	v_mov_b64_e32 v[66:67], v[2:3]
	v_mov_b64_e32 v[70:71], v[2:3]
	v_mov_b64_e32 v[110:111], v[2:3]
	v_mov_b64_e32 v[106:107], v[2:3]
	v_mov_b64_e32 v[62:63], v[2:3]
	v_mov_b64_e32 v[58:59], v[2:3]
	v_mov_b64_e32 v[22:23], v[2:3]
	v_mov_b64_e32 v[18:19], v[2:3]
	v_mov_b64_e32 v[134:135], v[2:3]
	v_mov_b64_e32 v[130:131], v[2:3]
	v_mov_b64_e32 v[118:119], v[2:3]
	v_mov_b64_e32 v[114:115], v[2:3]
	v_mov_b64_e32 v[78:79], v[2:3]
	v_mov_b64_e32 v[74:75], v[2:3]
	v_mov_b64_e32 v[30:31], v[2:3]
	v_mov_b64_e32 v[26:27], v[2:3]
	v_mov_b64_e32 v[126:127], v[2:3]
	v_mov_b64_e32 v[122:123], v[2:3]
	v_mov_b64_e32 v[102:103], v[2:3]
	v_mov_b64_e32 v[98:99], v[2:3]
	v_mov_b64_e32 v[54:55], v[2:3]
	v_mov_b64_e32 v[50:51], v[2:3]
	v_mov_b64_e32 v[14:15], v[2:3]
	v_mov_b64_e32 v[10:11], v[2:3]
	v_lshl_or_b32 v149, s4, 6, v148
	s_mov_b32 s75, 0
	v_mov_b64_e32 v[32:33], v[0:1]
	v_mov_b64_e32 v[36:37], v[0:1]
	v_mov_b64_e32 v[80:81], v[0:1]
	v_mov_b64_e32 v[84:85], v[0:1]
	v_mov_b64_e32 v[92:93], v[0:1]
	v_mov_b64_e32 v[88:89], v[0:1]
	v_mov_b64_e32 v[44:45], v[0:1]
	v_mov_b64_e32 v[40:41], v[0:1]
	v_mov_b64_e32 v[64:65], v[0:1]
	v_mov_b64_e32 v[68:69], v[0:1]
	v_mov_b64_e32 v[108:109], v[0:1]
	v_mov_b64_e32 v[104:105], v[0:1]
	v_mov_b64_e32 v[60:61], v[0:1]
	v_mov_b64_e32 v[56:57], v[0:1]
	v_mov_b64_e32 v[20:21], v[0:1]
	v_mov_b64_e32 v[16:17], v[0:1]
	v_mov_b64_e32 v[132:133], v[0:1]
	v_mov_b64_e32 v[128:129], v[0:1]
	v_mov_b64_e32 v[116:117], v[0:1]
	v_mov_b64_e32 v[112:113], v[0:1]
	v_mov_b64_e32 v[76:77], v[0:1]
	v_mov_b64_e32 v[72:73], v[0:1]
	v_mov_b64_e32 v[28:29], v[0:1]
	v_mov_b64_e32 v[24:25], v[0:1]
	v_mov_b64_e32 v[124:125], v[0:1]
	v_mov_b64_e32 v[120:121], v[0:1]
	v_mov_b64_e32 v[100:101], v[0:1]
	v_mov_b64_e32 v[96:97], v[0:1]
	v_mov_b64_e32 v[52:53], v[0:1]
	v_mov_b64_e32 v[48:49], v[0:1]
	v_mov_b64_e32 v[12:13], v[0:1]
	v_mov_b64_e32 v[8:9], v[0:1]
	s_barrier
	s_branch .LBB0_282

; #define PG8_LAS __attribute__((address_space(3)))
; #define PG8_STAGE(bufoff, gbase, voff) do { _Pragma("unroll") for (int _i = 0; _i < 2; ++_i) \
;         __builtin_amdgcn_global_load_lds((const unsigned*)((const char*)(gbase) + (voff)[_i]), (PG8_LAS unsigned*)(lds + (bufoff) + ldsw + _i * 8192), 16, 0, 0); } while (0)
; #define PG8_WAIT_V(n) asm volatile("s_waitcnt vmcnt(" #n ")" ::: "memory")
; #define PG8_BAR __builtin_amdgcn_s_barrier()
;     __device__ __forceinline__ void operator()(f32x4 (&acc)[2][2][4][2], const Unit& u, int wr, int wc, int fr, int fq, PG8_LAS unsigned char* lds, int wid, int lane) const {
;         PG8_LAS float* tbl = (PG8_LAS float*)(lds + 131072 + 10240);
;         PG8_LAS unsigned char* st = lds + 131072 + wid * 1280;
;         PG8_LAS float* X = (PG8_LAS float*)(lds + 131072 + 11264);
;         const int grow0 = 254 * u.pm - 2;
;         { const int t = wid * 64 + lane; if (t < 256) { const int gr = grow0 + t; tbl[t] = (gr >= 0 && gr < 8192) ? row_rstd(ss, gr) : 0.f; } }
;         const int j0 = u.pn * 128 + wc * 32 + 8 * fq;
;         asm volatile("s_waitcnt lgkmcnt(0)" ::: "memory"); __builtin_amdgcn_s_barrier(); asm volatile("" ::: "memory");
; #pragma unroll
;         for (int ai = 0; ai < 2; ++ai)
; #pragma unroll
;             for (int m = 0; m < 4; ++m) { const float rs = tbl[ai * HALF + wr * 64 + m * 16 + fr];
; #pragma unroll
;                 for (int bj = 0; bj < 2; ++bj)
; #pragma unroll
;                     for (int n = 0; n < 2; ++n) acc[ai][bj][m][n] = acc[ai][bj][m][n] * rs; }
;         if (fr >= 14) {
; #pragma unroll
;             for (int ai = 0; ai < 2; ++ai) { const int b = 2 * ai + wr; if (b < 3) {
; template <class Epi, class Sched, bool ALIGN_EPI = false, bool SP2 = false>
; __device__ __forceinline__ void gemm_phase(PG8_LAS unsigned char* lds, const Gemm g, const Sched& S, const Epi& E) {
;     ...
;         PG8_STAGE(PG8_SB(0, 0), cB, voffB); PG8_STAGE(PG8_SB(0, 1), cB + hstep, voffB); PG8_STAGE(PG8_SA(0, 0), cA, voffA); PG8_STAGE(PG8_SA(0, 1), cA + hstep, voffA);
;         if (wr == 1) PG8_BAR;
;         PG8_WAIT_V(2); PG8_BAR;
;         PG8_STAGE(PG8_SB(1, 0), cB + kstep, voffB); PG8_STAGE(PG8_SA(1, 0), cA + kstep, voffA); PG8_STAGE(PG8_SB(1, 1), cB + hstep + kstep, voffB);
;         PG8_WAIT_V(6); PG8_BAR;
.LBB0_350:
	v_and_b32_e32 v26, 15, v0
	v_and_b32_e32 v28, 48, v0
	v_lshlrev_b32_e32 v30, 2, v26
	s_lshl_b32 s5, s2, 13
	v_lshl_or_b32 v29, v26, 6, v28
	v_and_b32_e32 v31, 32, v30
	v_bitop3_b32 v32, v29, s5, v31 bitop3:0xde
	s_lshl_b32 s5, s3, 5
	s_and_b32 s97, s5, 0x60
	s_lshl_b32 s5, s97, 7
	s_add_u32 s12, s28, 0x1a100000
	v_readlane_b32 s6, v252, 51
	v_bitop3_b32 v230, s5, v29, v31 bitop3:0xf6
	s_addc_u32 s13, s29, 0
	s_mul_i32 s5, s6, 0x20400
	s_add_u32 s16, s60, s5
	s_addc_u32 s17, s61, 0
	s_mul_i32 s5, s6, 0xac00
	s_add_u32 s22, s62, s5
	s_addc_u32 s23, s63, 0
	s_add_i32 m0, s93, 0x18000
	v_lshl_add_u64 v[8:9], v[8:9], 0, s[24:25]
	global_load_lds_dwordx4 v[8:9], off
	v_lshl_add_u64 v[8:9], v[10:11], 0, s[24:25]
	s_add_i32 m0, s93, 0x1a000
	s_add_i32 s10, s93, 0x8000
	global_load_lds_dwordx4 v[8:9], off
	v_lshl_add_u64 v[8:9], v[16:17], 0, s[24:25]
	s_mov_b32 m0, s10
	s_add_i32 s11, s93, 0xa000
	global_load_lds_dwordx4 v[8:9], off
	v_lshl_add_u64 v[8:9], v[18:19], 0, s[24:25]
	s_mov_b32 m0, s11
	v_readlane_b32 s7, v252, 52
	global_load_lds_dwordx4 v[8:9], off
	s_add_i32 m0, s93, 0x1c000
	v_lshl_add_u64 v[8:9], v[12:13], 0, s[24:25]
	global_load_lds_dwordx4 v[8:9], off
	v_lshl_add_u64 v[8:9], v[14:15], 0, s[24:25]
	s_add_i32 m0, s93, 0x1e000
	v_readlane_b32 s5, v252, 23
	global_load_lds_dwordx4 v[8:9], off
	s_waitcnt vmcnt(8)
	s_barrier
	s_cmpk_lt_u32 s4, 0x100
	v_add_u32_e32 v8, s5, v30
	s_cselect_b64 s[6:7], -1, 0
	v_mov_b32_e32 v9, s4
	s_movk_i32 s5, 0xffc0
	v_writelane_b32 v252, s6, 42
	v_bfi_b32 v231, s5, v9, v0
	s_movk_i32 s5, 0x100
	v_writelane_b32 v252, s7, 43
	s_mulk_i32 s3, 0x500
	v_cmp_gt_i32_e64 s[6:7], s5, v231
	s_add_i32 s3, s3, 0
	s_add_i32 s3, s3, 0x20000
	v_writelane_b32 v252, s6, 51
	s_and_b32 s52, s4, 0xffffff00
	v_lshrrev_b32_e32 v27, 1, v0
	v_writelane_b32 v252, s7, 52
	s_add_i32 s6, 0, 0x22c00
	s_cmp_lt_i32 s2, 3
	s_cselect_b64 s[4:5], -1, 0
	v_writelane_b32 v253, s4, 13
	s_lshl_b32 s7, s2, 11
	s_lshl_b32 s42, s97, 2
	v_writelane_b32 v253, s5, 14
	s_or_b32 s4, s42, s7
	v_and_b32_e32 v27, 24, v27
	s_add_i32 s4, s4, s6
	v_lshlrev_b32_e32 v9, 10, v26
	v_lshlrev_b32_e32 v10, 2, v27
	s_cmp_lt_i32 s2, 1
	v_add3_u32 v11, s4, v9, v10
	s_cselect_b64 s[4:5], -1, 0
	v_writelane_b32 v253, s4, 15
	s_cmp_gt_i32 s2, 0
	v_cmp_lt_u32_e64 s[40:41], 13, v26
	v_writelane_b32 v253, s5, 16
	s_cselect_b64 s[4:5], -1, 0
	s_add_i32 s6, s6, s7
	s_and_b64 s[78:79], s[40:41], s[4:5]
	s_add_i32 s42, s42, s6
	s_cmp_gt_i32 s2, -2
	s_cselect_b64 s[4:5], -1, 0
	v_add_u32_e32 v233, 0xffffc800, v11
	v_add_u32_e32 v234, 0xffffd800, v11
	v_mov_b32_e32 v11, s3
	s_movk_i32 s3, 0x50
	v_bfe_u32 v13, v0, 2, 4
	s_and_b64 s[80:81], s[40:41], s[4:5]
	v_mad_u32_u24 v12, v26, s3, v11
	v_mad_u32_u24 v11, v13, s3, v11
	v_and_b32_e32 v0, 3, v0
	s_cmp_gt_i32 s2, -1
	v_readlane_b32 s3, v253, 10
	v_lshl_or_b32 v235, s2, 6, v13
	v_lshlrev_b32_e32 v13, 4, v0
	v_lshlrev_b32_e32 v182, 3, v0
	v_add3_u32 v0, s42, v9, v10
	s_cselect_b64 s[82:83], -1, 0
	s_abs_i32 s75, s3
	v_add_u32_e32 v236, 0xffffc000, v0
	v_add_u32_e32 v237, 0xffffd000, v0
	v_cvt_f32_u32_e32 v0, s75
	s_movk_i32 s2, 0xff81
	v_cmp_lt_i32_e64 s[44:45], s2, v235
	s_movk_i32 s2, 0xff71
	v_rcp_iflag_f32_e32 v0, v0
	v_cmp_lt_i32_e64 s[46:47], s2, v235
	s_movk_i32 s2, 0xff61
	v_cmp_lt_i32_e64 s[4:5], s2, v235
	v_mul_f32_e32 v0, 0x4f7ffffe, v0
	v_cvt_u32_f32_e32 v0, v0
	s_movk_i32 s2, 0xff51
	v_cmp_lt_i32_e64 s[6:7], s2, v235
	s_ashr_i32 s2, s3, 31
	v_writelane_b32 v253, s2, 17
	s_sub_i32 s2, 0, s75
	v_readfirstlane_b32 s3, v0
	v_add_u32_e32 v0, v22, v20
	s_mul_i32 s2, s2, s3
	v_add_lshl_u32 v0, v0, v21, 1
	s_waitcnt vmcnt(6)
	s_mul_hi_u32 s2, s3, s2
	v_lshl_add_u64 v[184:185], s[48:49], 0, v[0:1]
	v_add_u32_e32 v0, v25, v23
	s_add_i32 s2, s3, s2
	v_add_lshl_u32 v0, v0, v24, 1
	v_or_b32_e32 v232, s97, v27
	s_mov_b32 s74, 0
	v_cmp_lt_i32_e64 s[42:43], 1, v235
	v_writelane_b32 v253, s2, 18
	v_lshl_add_u64 v[186:187], s[48:49], 0, v[0:1]
	v_add_u32_e32 v238, 0, v32
	v_add_u32_e32 v239, s52, v8
	v_add_u32_e32 v240, v12, v28
	v_add_u32_e32 v241, v11, v13
	s_barrier
	s_branch .LBB0_353

; #define PG8_LAS __attribute__((address_space(3)))
; #define PG8_STAGE(bufoff, gbase, voff) do { _Pragma("unroll") for (int _i = 0; _i < 2; ++_i) \
;         __builtin_amdgcn_global_load_lds((const unsigned*)((const char*)(gbase) + (voff)[_i]), (PG8_LAS unsigned*)(lds + (bufoff) + ldsw + _i * 8192), 16, 0, 0); } while (0)
; #define PG8_WAIT_V(n) asm volatile("s_waitcnt vmcnt(" #n ")" ::: "memory")
; #define PG8_BAR __builtin_amdgcn_s_barrier()
;     __device__ __forceinline__ void operator()(const f32x4 (&acc)[2][2][4][2], const Unit& u, int wr, int wc, int fr, int fq, PG8_LAS unsigned char* lds, int wid, int lane) const {
;         PG8_LAS float* tbl = (PG8_LAS float*)(lds + 131072 + 10240);
;         PG8_LAS unsigned char* st = lds + 131072 + wid * 1280;
;         { const int t = wid * 64 + lane; if (t < 256) { const int col = u.pn * BM + t; float r = row_rstd(ss, col);
;             if (u.pm < 8) { const float lg = -log2f(1.0f - exp2f(-5.0f - (float)u.pm)); r *= exp2f(lg * (float)((col & 127) + 1)) * 0.0625f; } tbl[t] = r; } }
;         asm volatile("s_waitcnt lgkmcnt(0)" ::: "memory"); __builtin_amdgcn_s_barrier(); asm volatile("" ::: "memory");
;         f32x4 cr[2][2];
; #pragma unroll
;         for (int bj = 0; bj < 2; ++bj)
; #pragma unroll
;             for (int n = 0; n < 2; ++n) cr[bj][n] = *(const PG8_LAS f32x4*)(tbl + bj * HALF + wc * 32 + 8 * fq + 4 * n);
;         bf16_t* obase = O + (size_t)(u.pm * BM + wr * 64 + (lane >> 2)) * ldc + u.pn * BM + wc * 32 + 8 * (lane & 3);
; template <class Epi, class Sched, bool ALIGN_EPI = false, bool SP2 = false>
; __device__ __forceinline__ void gemm_phase(PG8_LAS unsigned char* lds, const Gemm g, const Sched& S, const Epi& E) {
;     ...
;         PG8_STAGE(PG8_SB(0, 0), cB, voffB); PG8_STAGE(PG8_SB(0, 1), cB + hstep, voffB); PG8_STAGE(PG8_SA(0, 0), cA, voffA); PG8_STAGE(PG8_SA(0, 1), cA + hstep, voffA);
;         if (wr == 1) PG8_BAR;
;         PG8_WAIT_V(2); PG8_BAR;
;         PG8_STAGE(PG8_SB(1, 0), cB + kstep, voffB); PG8_STAGE(PG8_SA(1, 0), cA + kstep, voffA); PG8_STAGE(PG8_SB(1, 1), cB + hstep + kstep, voffB);
;         PG8_WAIT_V(6); PG8_BAR;
.LBB0_453:
	s_add_i32 m0, s46, 0x18000
	v_lshl_add_u64 v[8:9], v[8:9], 0, s[24:25]
	global_load_lds_dwordx4 v[8:9], off
	v_lshl_add_u64 v[8:9], v[10:11], 0, s[24:25]
	s_add_i32 m0, s46, 0x1a000
	s_add_i32 s72, s46, 0x8000
	global_load_lds_dwordx4 v[8:9], off
	v_lshl_add_u64 v[8:9], v[16:17], 0, s[24:25]
	s_mov_b32 m0, s72
	s_add_i32 s73, s46, 0xa000
	global_load_lds_dwordx4 v[8:9], off
	v_lshl_add_u64 v[8:9], v[18:19], 0, s[24:25]
	s_mov_b32 m0, s73
	v_and_b32_e32 v26, 15, v0
	global_load_lds_dwordx4 v[8:9], off
	s_add_i32 m0, s46, 0x1c000
	v_lshl_add_u64 v[8:9], v[12:13], 0, s[24:25]
	global_load_lds_dwordx4 v[8:9], off
	v_lshl_add_u64 v[8:9], v[14:15], 0, s[24:25]
	s_add_i32 m0, s46, 0x1e000
	v_and_b32_e32 v28, 48, v0
	global_load_lds_dwordx4 v[8:9], off
	s_waitcnt vmcnt(8)
	s_barrier
	v_lshlrev_b32_e32 v30, 2, v0
	s_and_b32 s6, s5, 3
	s_lshl_b32 s3, s4, 13
	v_lshl_or_b32 v29, v26, 6, v28
	v_and_b32_e32 v30, 32, v30
	v_bitop3_b32 v31, v29, s3, v30 bitop3:0xde
	s_lshl_b32 s7, s6, 5
	s_lshl_b32 s3, s6, 12
	s_cmpk_lt_u32 s2, 0x100
	s_cselect_b64 s[12:13], -1, 0
	s_and_b32 s16, s2, 0xffffffc0
	v_mov_b32_e32 v8, s2
	s_movk_i32 s2, 0xffc0
	v_and_b32_e32 v27, 63, v0
	v_bfi_b32 v163, s2, v8, v0
	v_mov_b32_e32 v8, 0x7f
	s_mulk_i32 s5, 0x500
	v_bitop3_b32 v8, s16, v8, v27 bitop3:0xc8
	s_add_i32 s5, s5, 0
	v_add_u32_e32 v8, 1, v8
	s_add_i32 s5, s5, 0x20000
	v_bfe_u32 v10, v0, 2, 4
	v_cvt_f32_ubyte0_e32 v164, v8
	v_lshlrev_b32_e32 v8, 1, v0
	v_lshl_or_b32 v166, s4, 6, v10
	v_and_b32_e32 v0, 3, v0
	v_mov_b32_e32 v11, s5
	s_movk_i32 s4, 0x50
	v_and_b32_e32 v9, 0x60, v8
	v_lshlrev_b32_e32 v8, 3, v0
	v_mad_u32_u24 v12, v26, s4, v11
	v_mad_u32_u24 v10, v10, s4, v11
	v_lshlrev_b32_e32 v11, 4, v0
	v_add_u32_e32 v0, v25, v23
	v_add_lshl_u32 v0, v0, v24, 1
	s_waitcnt vmcnt(6)
	v_readlane_b32 s16, v252, 23
	s_lshl_b32 s6, s6, 7
	v_lshl_add_u64 v[158:159], s[48:49], 0, v[0:1]
	v_add_u32_e32 v0, v22, v20
	s_movk_i32 s2, 0x100
	s_add_i32 s6, s16, s6
	v_add_lshl_u32 v0, v0, v21, 1
	v_bitop3_b32 v162, v29, s3, v30 bitop3:0xde
	v_cmp_gt_i32_e64 s[2:3], s2, v163
	v_lshl_add_u32 v165, v163, 2, s16
	s_mul_i32 s16, s26, 0xa0
	s_mov_b32 s17, s21
	v_lshl_add_u64 v[160:161], s[48:49], 0, v[0:1]
	s_mov_b32 s74, 0
	v_add_u32_e32 v167, 0, v31
	v_add_u32_e32 v168, s6, v9
	s_lshl_b32 s20, s7, 1
	v_lshlrev_b32_e32 v0, 1, v8
	v_add_u32_e32 v169, v12, v28
	v_add_u32_e32 v170, v10, v11
	s_barrier
	s_branch .LBB0_456

; #define PG8_LAS __attribute__((address_space(3)))
; #define PG8_STAGE(bufoff, gbase, voff) do { _Pragma("unroll") for (int _i = 0; _i < 2; ++_i) \
;         __builtin_amdgcn_global_load_lds((const unsigned*)((const char*)(gbase) + (voff)[_i]), (PG8_LAS unsigned*)(lds + (bufoff) + ldsw + _i * 8192), 16, 0, 0); } while (0)
; #define PG8_WAIT_V(n) asm volatile("s_waitcnt vmcnt(" #n ")" ::: "memory")
; #define PG8_BAR __builtin_amdgcn_s_barrier()
;     __device__ __forceinline__ void operator()(const f32x4 (&acc)[2][2][4][2], const Unit& u, int wr, int wc, int fr, int fq, PG8_LAS unsigned char* lds, int wid, int lane) const {
;         const int colt = u.pn * BM; const int col0 = colt + wc * 32 + 8 * fq;
;         PG8_LAS float* tbl = (PG8_LAS float*)(lds + 131072 + 10240);
;         PG8_LAS unsigned char* st = lds + 131072 + wid * 1280;
;         { const int t = wid * 64 + lane; if (t < 256) tbl[t] = row_rstd(ss, u.pm * BM + t); }
;         f32x4 bv[2][2];
; #pragma unroll
;         for (int bj = 0; bj < 2; ++bj)
; #pragma unroll
;             for (int n = 0; n < 2; ++n) bv[bj][n] = bias ? *(const f32x4*)(bias + col0 + bj * HALF + 4 * n) : (f32x4){0.f, 0.f, 0.f, 0.f};
;         const float cs = (mode == 2 && colt < 2048) ? 0.125f : 1.0f;
;         asm volatile("s_waitcnt lgkmcnt(0)" ::: "memory"); __builtin_amdgcn_s_barrier(); asm volatile("" ::: "memory");
;         bf16_t* obase = O + (size_t)(u.pm * BM + wr * 64 + (lane >> 2)) * ldc + colt + wc * 32 + 8 * (lane & 3);
; template <class Epi, class Sched, bool ALIGN_EPI = false, bool SP2 = false>
; __device__ __forceinline__ void gemm_phase(PG8_LAS unsigned char* lds, const Gemm g, const Sched& S, const Epi& E) {
;     ...
;         PG8_STAGE(PG8_SB(0, 0), cB, voffB); PG8_STAGE(PG8_SB(0, 1), cB + hstep, voffB); PG8_STAGE(PG8_SA(0, 0), cA, voffA); PG8_STAGE(PG8_SA(0, 1), cA + hstep, voffA);
;         if (wr == 1) PG8_BAR;
;         PG8_WAIT_V(2); PG8_BAR;
;         PG8_STAGE(PG8_SB(1, 0), cB + kstep, voffB); PG8_STAGE(PG8_SA(1, 0), cA + kstep, voffA); PG8_STAGE(PG8_SB(1, 1), cB + hstep + kstep, voffB);
;         PG8_WAIT_V(6); PG8_BAR;
.LBB0_486:
	s_lshl_b32 s10, s3, 5
	s_and_b32 s20, s10, 0x60
	v_readlane_b32 s10, v252, 47
	s_lshl_b32 s5, s2, 13
	s_lshl_b32 s12, s20, 7
	v_readlane_b32 s11, v252, 48
	s_cmp_lg_u64 s[10:11], 0
	s_cselect_b64 s[10:11], -1, 0
	s_add_i32 m0, s45, 0x18000
	v_lshl_add_u64 v[16:17], v[16:17], 0, s[24:25]
	global_load_lds_dwordx4 v[16:17], off
	v_lshl_add_u64 v[12:13], v[12:13], 0, s[24:25]
	s_add_i32 m0, s45, 0x1a000
	s_add_i32 s53, s45, 0x8000
	global_load_lds_dwordx4 v[12:13], off
	v_lshl_add_u64 v[12:13], v[14:15], 0, s[24:25]
	s_mov_b32 m0, s53
	s_add_i32 s72, s45, 0xa000
	global_load_lds_dwordx4 v[12:13], off
	v_lshl_add_u64 v[12:13], v[18:19], 0, s[24:25]
	s_mov_b32 m0, s72
	v_lshl_add_u64 v[10:11], v[10:11], 0, s[24:25]
	global_load_lds_dwordx4 v[12:13], off
	s_add_i32 m0, s45, 0x1c000
	v_lshl_add_u64 v[8:9], v[8:9], 0, s[24:25]
	global_load_lds_dwordx4 v[10:11], off
	s_add_i32 m0, s45, 0x1e000
	v_and_b32_e32 v10, 48, v0
	global_load_lds_dwordx4 v[8:9], off
	s_waitcnt vmcnt(8)
	s_barrier
	v_and_b32_e32 v9, 15, v0
	v_lshlrev_b32_e32 v12, 2, v9
	v_lshl_or_b32 v11, v9, 6, v10
	v_and_b32_e32 v13, 32, v12
	v_bitop3_b32 v14, v11, s5, v13 bitop3:0xde
	s_cmpk_lt_u32 s4, 0x100
	v_readlane_b32 s5, v253, 10
	v_bitop3_b32 v164, s12, v11, v13 bitop3:0xf6
	s_cselect_b64 s[12:13], -1, 0
	s_abs_i32 s73, s5
	v_cvt_f32_u32_e32 v13, s73
	v_lshrrev_b32_e32 v8, 1, v0
	v_and_or_b32 v165, v8, 24, s20
	v_mov_b32_e32 v8, s4
	s_movk_i32 s4, 0xffc0
	v_bfi_b32 v166, s4, v8, v0
	s_movk_i32 s4, 0x100
	s_mulk_i32 s3, 0x500
	v_bfe_u32 v11, v0, 2, 4
	v_rcp_iflag_f32_e32 v13, v13
	v_cmp_gt_i32_e64 s[38:39], s4, v166
	v_readlane_b32 s4, v252, 23
	s_add_i32 s3, s3, 0
	v_lshl_or_b32 v168, s2, 6, v11
	s_lshl_b32 s2, s2, 8
	s_add_i32 s3, s3, 0x20000
	s_add_i32 s2, s4, s2
	v_and_b32_e32 v0, 3, v0
	v_add_u32_e32 v169, s2, v12
	v_mov_b32_e32 v12, s3
	s_movk_i32 s2, 0x50
	v_lshlrev_b32_e32 v8, 3, v0
	v_mad_u32_u24 v9, v9, s2, v12
	v_mad_u32_u24 v11, v11, s2, v12
	v_lshlrev_b32_e32 v12, 4, v0
	v_mul_f32_e32 v0, 0x4f7ffffe, v13
	v_cvt_u32_f32_e32 v0, v0
	s_sub_i32 s2, 0, s73
	s_waitcnt vmcnt(6)
	v_lshl_add_u32 v167, v166, 2, s4
	v_readfirstlane_b32 s3, v0
	v_add_u32_e32 v0, v22, v20
	v_add_lshl_u32 v0, v0, v21, 1
	s_mul_i32 s2, s2, s3
	v_lshl_add_u64 v[158:159], s[48:49], 0, v[0:1]
	v_add_u32_e32 v0, v25, v23
	s_mul_hi_u32 s2, s3, s2
	v_add_lshl_u32 v0, v0, v24, 1
	s_ashr_i32 s74, s5, 31
	s_mov_b32 s75, 0
	s_add_i32 s76, s3, s2
	s_mul_i32 s16, s26, 0xa0
	s_mov_b32 s17, s21
	v_lshl_add_u64 v[160:161], s[48:49], 0, v[0:1]
	v_add_u32_e32 v170, 0, v14
	s_lshl_b32 s20, s20, 1
	v_lshlrev_b32_e32 v0, 1, v8
	v_add_u32_e32 v171, v9, v10
	v_add_u32_e32 v172, v11, v12
	s_barrier
	s_branch .LBB0_489
